# P4 output published write-through (sc1 stores) and the barrier behind P4 without the release L2 write-back
# speedup vs baseline: 1.0033x; 1.0033x over previous
;     __device__ __forceinline__ const char* b(const Unit& u) const { return (const char*)Bt + (size_t)u.pn * 2 * hB() + (size_t)(u.pm >> gshift) * goff; }
;     __device__ __forceinline__ const char* b(const Unit& u) const { return (const char*)Bt + (size_t)((u.pn >> 4) * 4096 + (u.pn & 15) * 16) * 1024 * 2 + (size_t)(u.pm >> 1) * 512; }
;     __device__ __forceinline__ const char* b(const Unit& u) const { return (const char*)Bt + ((size_t)(((u.pm >> 4) * 1024 + u.pn * 256) * 16 + (u.pm & 15)) * 512) * 2; }
;     __device__ __forceinline__ void operator()(const f32x4 (&acc)[2][2][4][2], const Unit& u, int wr, int wc, int fr, int fq) const {
;     ...
; #pragma unroll
;         for (int ai = 0; ai < 2; ++ai)
; #pragma unroll
;             for (int m = 0; m < 4; ++m) { const int r = row0 + ai * HALF + m * 16; const size_t off = (size_t)r * ldc + col0; float s = 0.f;
; #pragma unroll
;                 for (int bj = 0; bj < 2; ++bj) { const u32x4 b = bv[ai][m][bj];
;                     f32x4 o0, o1;
;                     o0[0] = __builtin_fmaf(acc[ai][bj][m][0][0], asc, __builtin_bit_cast(float, b.x << 16)); o0[1] = __builtin_fmaf(acc[ai][bj][m][0][1], asc, __builtin_bit_cast(float, b.x & 0xffff0000u));
;                     o0[2] = __builtin_fmaf(acc[ai][bj][m][0][2], asc, __builtin_bit_cast(float, b.y << 16)); o0[3] = __builtin_fmaf(acc[ai][bj][m][0][3], asc, __builtin_bit_cast(float, b.y & 0xffff0000u));
;                     o1[0] = __builtin_fmaf(acc[ai][bj][m][1][0], asc, __builtin_bit_cast(float, b.z << 16)); o1[1] = __builtin_fmaf(acc[ai][bj][m][1][1], asc, __builtin_bit_cast(float, b.z & 0xffff0000u));
;                     o1[2] = __builtin_fmaf(acc[ai][bj][m][1][2], asc, __builtin_bit_cast(float, b.w << 16)); o1[3] = __builtin_fmaf(acc[ai][bj][m][1][3], asc, __builtin_bit_cast(float, b.w & 0xffff0000u));
;                     s += ((o0[0] * o0[0] + o0[1] * o0[1]) + (o0[2] * o0[2] + o0[3] * o0[3])) + ((o1[0] * o1[0] + o1[1] * o1[1]) + (o1[2] * o1[2] + o1[3] * o1[3]));
;                     u32x4 w; w.x = cvt_pk_bf16(o0[0], o0[1]); w.y = cvt_pk_bf16(o0[2], o0[3]); w.z = cvt_pk_bf16(o1[0], o1[1]); w.w = cvt_pk_bf16(o1[2], o1[3]);
;                     *(u32x4*)(outb + off + bj * HALF) = w; }
;                 s += __shfl_xor(s, 16); s += __shfl_xor(s, 32);
;                 if (fq == 0) atomicAdd(ssq + r, s); }
mk_p4_endB:
	s_waitcnt vmcnt(0) lgkmcnt(0)
	v_lshlrev_b32_e32 v222, 16, v192
	v_and_b32_e32 v192, 0xffff0000, v192
	v_lshlrev_b32_e32 v223, 16, v193
	v_and_b32_e32 v193, 0xffff0000, v193
	v_lshlrev_b32_e32 v224, 16, v194
	v_and_b32_e32 v194, 0xffff0000, v194
	v_lshlrev_b32_e32 v225, 16, v195
	v_and_b32_e32 v195, 0xffff0000, v195
	v_lshlrev_b32_e32 v226, 16, v214
	v_and_b32_e32 v214, 0xffff0000, v214
	v_fmac_f32_e32 v192, 0x3d000000, v125
	v_fmac_f32_e32 v193, 0x3d000000, v127
	v_fmac_f32_e32 v194, 0x3d000000, v121
	v_fmac_f32_e32 v195, 0x3d000000, v123
	v_fmac_f32_e32 v222, 0x3d000000, v124
	v_fmac_f32_e32 v223, 0x3d000000, v126
	v_fmac_f32_e32 v224, 0x3d000000, v120
	v_fmac_f32_e32 v225, 0x3d000000, v122
	v_fmac_f32_e32 v226, 0x3d000000, v116
	v_mul_f32_e32 v116, v192, v192
	v_mul_f32_e32 v124, v193, v193
	v_mul_f32_e32 v125, v194, v194
	v_mul_f32_e32 v126, v195, v195
	v_fmac_f32_e32 v214, 0x3d000000, v117
	v_lshlrev_b32_e32 v117, 16, v215
	v_fmac_f32_e32 v116, v222, v222
	v_fmac_f32_e32 v124, v223, v223
	v_fmac_f32_e32 v125, v224, v224
	v_fmac_f32_e32 v126, v225, v225
	v_fmac_f32_e32 v117, 0x3d000000, v118
	v_and_b32_e32 v118, 0xffff0000, v215
	v_add_f32_e32 v116, v116, v124
	v_add_f32_e32 v124, v125, v126
	v_fmac_f32_e32 v118, 0x3d000000, v119
	v_lshlrev_b32_e32 v119, 16, v216
	v_and_b32_e32 v126, 0xffff0000, v216
	v_cvt_pk_bf16_f32 v120, v222, v192
	v_fmac_f32_e32 v119, 0x3d000000, v112
	v_fmac_f32_e32 v126, 0x3d000000, v113
	v_and_b32_e32 v192, 0xffff0000, v217
	v_mul_f32_e32 v112, v214, v214
	v_mul_f32_e32 v113, v118, v118
	v_lshlrev_b32_e32 v127, 16, v217
	v_fmac_f32_e32 v192, 0x3d000000, v115
	v_fmac_f32_e32 v112, v226, v226
	v_fmac_f32_e32 v113, v117, v117
	v_fmac_f32_e32 v127, 0x3d000000, v114
	v_add_f32_e32 v112, v112, v113
	v_mul_f32_e32 v113, v126, v126
	v_mul_f32_e32 v114, v192, v192
	v_fmac_f32_e32 v113, v119, v119
	v_fmac_f32_e32 v114, v127, v127
	v_add_f32_e32 v113, v113, v114
	v_add_f32_e32 v116, v116, v124
	v_add_f32_e32 v112, v112, v113
	v_and_b32_e32 v114, 64, v252
	v_cvt_pk_bf16_f32 v121, v223, v193
	v_add_f32_e32 v113, v116, v112
	v_xor_b32_e32 v112, 16, v252
	v_add_u32_e32 v193, 64, v114
	v_cmp_lt_i32_e64 s[6:7], v112, v193
	v_cvt_pk_bf16_f32 v122, v224, v194
	v_lshl_add_u64 v[114:115], s[74:75], 0, v[220:221]
	v_lshl_add_u64 v[124:125], v[114:115], 0, v[218:219]
	v_cndmask_b32_e64 v112, v252, v112, s[6:7]
	v_lshlrev_b32_e32 v112, 2, v112
	ds_bpermute_b32 v194, v112, v113
	v_cvt_pk_bf16_f32 v123, v225, v195
	global_store_dwordx4 v[124:125], v[120:123], off sc1
	v_cvt_pk_bf16_f32 v116, v226, v214
	v_cvt_pk_bf16_f32 v117, v117, v118
	s_waitcnt lgkmcnt(0)
	v_add_f32_e32 v114, v113, v194
	v_xor_b32_e32 v113, 32, v252
	v_cmp_lt_i32_e64 s[6:7], v113, v193
	v_cvt_pk_bf16_f32 v118, v119, v126
	v_cvt_pk_bf16_f32 v119, v127, v192
	global_store_dwordx4 v[124:125], v[116:119], off offset:256 sc1
	s_nop 0
	v_cndmask_b32_e64 v113, v252, v113, s[6:7]
	v_lshlrev_b32_e32 v113, 2, v113
	ds_bpermute_b32 v115, v113, v114
	s_and_saveexec_b64 s[6:7], vcc
	s_cbranch_execz .LBB0_628
	v_lshl_add_u64 v[116:117], v[212:213], 2, s[66:67]
	s_waitcnt lgkmcnt(0)
	v_add_f32_e32 v114, v114, v115
	global_atomic_add_f32 v[116:117], v114, off
.LBB0_628:
	s_or_b64 exec, exec, s[6:7]
	v_lshlrev_b32_e32 v116, 16, v180
	v_fmac_f32_e32 v116, 0x3d000000, v108
	v_and_b32_e32 v108, 0xffff0000, v180
	v_fmac_f32_e32 v108, 0x3d000000, v109
	v_lshlrev_b32_e32 v109, 16, v181
	v_fmac_f32_e32 v109, 0x3d000000, v110
	v_and_b32_e32 v110, 0xffff0000, v181
	v_fmac_f32_e32 v110, 0x3d000000, v111
	v_lshlrev_b32_e32 v111, 16, v182
	v_and_b32_e32 v117, 0xffff0000, v182
	v_fmac_f32_e32 v111, 0x3d000000, v104
	v_fmac_f32_e32 v117, 0x3d000000, v105
	v_and_b32_e32 v119, 0xffff0000, v183
	v_mul_f32_e32 v104, v108, v108
	v_mul_f32_e32 v105, v110, v110
	v_lshlrev_b32_e32 v118, 16, v183
	v_fmac_f32_e32 v119, 0x3d000000, v107
	v_fmac_f32_e32 v104, v116, v116
	v_fmac_f32_e32 v105, v109, v109
	v_fmac_f32_e32 v118, 0x3d000000, v106
	v_add_f32_e32 v104, v104, v105
	v_mul_f32_e32 v105, v117, v117
	v_mul_f32_e32 v106, v119, v119
	v_fmac_f32_e32 v105, v111, v111
	v_fmac_f32_e32 v106, v118, v118
	v_add_f32_e32 v105, v105, v106
	v_add_f32_e32 v120, v104, v105
	v_cvt_pk_bf16_f32 v104, v116, v108
	v_lshlrev_b32_e32 v108, 16, v176
	v_cvt_pk_bf16_f32 v105, v109, v110
	v_fmac_f32_e32 v108, 0x3d000000, v100
	v_and_b32_e32 v100, 0xffff0000, v176
	v_and_b32_e32 v109, 0xffff0000, v177
	v_cvt_pk_bf16_f32 v106, v111, v117
	v_fmac_f32_e32 v100, 0x3d000000, v101
	v_lshlrev_b32_e32 v101, 16, v177
	v_fmac_f32_e32 v109, 0x3d000000, v103
	v_lshlrev_b32_e32 v110, 16, v178
	v_and_b32_e32 v111, 0xffff0000, v178
	v_fmac_f32_e32 v101, 0x3d000000, v102
	v_fmac_f32_e32 v110, 0x3d000000, v96
	v_fmac_f32_e32 v111, 0x3d000000, v97
	v_and_b32_e32 v117, 0xffff0000, v179
	v_mul_f32_e32 v96, v100, v100
	v_mul_f32_e32 v97, v109, v109
	v_lshlrev_b32_e32 v116, 16, v179
	v_fmac_f32_e32 v117, 0x3d000000, v99
	v_fmac_f32_e32 v96, v108, v108
	v_fmac_f32_e32 v97, v101, v101
	v_fmac_f32_e32 v116, 0x3d000000, v98
	v_add_f32_e32 v96, v96, v97
	v_mul_f32_e32 v97, v111, v111
	v_mul_f32_e32 v98, v117, v117
	v_fmac_f32_e32 v97, v110, v110
	v_fmac_f32_e32 v98, v116, v116
	v_add_f32_e32 v97, v97, v98
	v_add_f32_e32 v96, v96, v97
	v_add_f32_e32 v99, v120, v96
	v_cvt_pk_bf16_f32 v107, v118, v119
	ds_bpermute_b32 v118, v112, v99
	s_waitcnt lgkmcnt(1)
	v_lshlrev_b64 v[114:115], 11, v[210:211]
	v_lshl_add_u64 v[96:97], v[114:115], 1, s[74:75]
	v_lshl_add_u64 v[102:103], v[196:197], 1, v[96:97]
	global_store_dwordx4 v[102:103], v[104:107], off sc1
	s_waitcnt lgkmcnt(0)
	v_add_f32_e32 v96, v99, v118
	ds_bpermute_b32 v97, v113, v96
	v_cvt_pk_bf16_f32 v98, v108, v100
	v_cvt_pk_bf16_f32 v99, v101, v109
	v_cvt_pk_bf16_f32 v100, v110, v111
	v_cvt_pk_bf16_f32 v101, v116, v117
	global_store_dwordx4 v[102:103], v[98:101], off offset:256 sc1
	s_and_saveexec_b64 s[6:7], vcc
	s_cbranch_execz .LBB0_630
	v_lshl_add_u64 v[98:99], v[210:211], 2, s[66:67]
	s_waitcnt lgkmcnt(0)
	v_add_f32_e32 v96, v96, v97
	global_atomic_add_f32 v[98:99], v96, off
;     __device__ __forceinline__ const char* b(const Unit& u) const { return (const char*)Bt + (size_t)u.pn * 2 * hB() + (size_t)(u.pm >> gshift) * goff; }
;     __device__ __forceinline__ const char* b(const Unit& u) const { return (const char*)Bt + (size_t)((u.pn >> 4) * 4096 + (u.pn & 15) * 16) * 1024 * 2 + (size_t)(u.pm >> 1) * 512; }
;     __device__ __forceinline__ const char* b(const Unit& u) const { return (const char*)Bt + ((size_t)(((u.pm >> 4) * 1024 + u.pn * 256) * 16 + (u.pm & 15)) * 512) * 2; }
;     __device__ __forceinline__ void operator()(const f32x4 (&acc)[2][2][4][2], const Unit& u, int wr, int wc, int fr, int fq) const {
;     ...
; #pragma unroll
;         for (int ai = 0; ai < 2; ++ai)
; #pragma unroll
;             for (int m = 0; m < 4; ++m) { const int r = row0 + ai * HALF + m * 16; const size_t off = (size_t)r * ldc + col0; float s = 0.f;
; #pragma unroll
;                 for (int bj = 0; bj < 2; ++bj) { const u32x4 b = bv[ai][m][bj];
;                     f32x4 o0, o1;
;                     o0[0] = __builtin_fmaf(acc[ai][bj][m][0][0], asc, __builtin_bit_cast(float, b.x << 16)); o0[1] = __builtin_fmaf(acc[ai][bj][m][0][1], asc, __builtin_bit_cast(float, b.x & 0xffff0000u));
;                     o0[2] = __builtin_fmaf(acc[ai][bj][m][0][2], asc, __builtin_bit_cast(float, b.y << 16)); o0[3] = __builtin_fmaf(acc[ai][bj][m][0][3], asc, __builtin_bit_cast(float, b.y & 0xffff0000u));
;                     o1[0] = __builtin_fmaf(acc[ai][bj][m][1][0], asc, __builtin_bit_cast(float, b.z << 16)); o1[1] = __builtin_fmaf(acc[ai][bj][m][1][1], asc, __builtin_bit_cast(float, b.z & 0xffff0000u));
;                     o1[2] = __builtin_fmaf(acc[ai][bj][m][1][2], asc, __builtin_bit_cast(float, b.w << 16)); o1[3] = __builtin_fmaf(acc[ai][bj][m][1][3], asc, __builtin_bit_cast(float, b.w & 0xffff0000u));
;                     s += ((o0[0] * o0[0] + o0[1] * o0[1]) + (o0[2] * o0[2] + o0[3] * o0[3])) + ((o1[0] * o1[0] + o1[1] * o1[1]) + (o1[2] * o1[2] + o1[3] * o1[3]));
;                     u32x4 w; w.x = cvt_pk_bf16(o0[0], o0[1]); w.y = cvt_pk_bf16(o0[2], o0[3]); w.z = cvt_pk_bf16(o1[0], o1[1]); w.w = cvt_pk_bf16(o1[2], o1[3]);
;                     *(u32x4*)(outb + off + bj * HALF) = w; }
;                 s += __shfl_xor(s, 16); s += __shfl_xor(s, 32);
;                 if (fq == 0) atomicAdd(ssq + r, s); }
.LBB0_630:
	s_or_b64 exec, exec, s[6:7]
	v_lshlrev_b32_e32 v98, 16, v172
	v_fmac_f32_e32 v98, 0x3d000000, v92
	v_and_b32_e32 v92, 0xffff0000, v172
	v_fmac_f32_e32 v92, 0x3d000000, v93
	v_lshlrev_b32_e32 v93, 16, v173
	v_fmac_f32_e32 v93, 0x3d000000, v94
	v_and_b32_e32 v94, 0xffff0000, v173
	v_fmac_f32_e32 v94, 0x3d000000, v95
	v_lshlrev_b32_e32 v95, 16, v174
	v_and_b32_e32 v99, 0xffff0000, v174
	v_fmac_f32_e32 v95, 0x3d000000, v88
	v_fmac_f32_e32 v99, 0x3d000000, v89
	v_and_b32_e32 v101, 0xffff0000, v175
	v_mul_f32_e32 v88, v92, v92
	v_mul_f32_e32 v89, v94, v94
	v_lshlrev_b32_e32 v100, 16, v175
	v_fmac_f32_e32 v101, 0x3d000000, v91
	v_fmac_f32_e32 v88, v98, v98
	v_fmac_f32_e32 v89, v93, v93
	v_fmac_f32_e32 v100, 0x3d000000, v90
	v_add_f32_e32 v88, v88, v89
	v_mul_f32_e32 v89, v99, v99
	v_mul_f32_e32 v90, v101, v101
	v_fmac_f32_e32 v89, v95, v95
	v_fmac_f32_e32 v90, v100, v100
	v_add_f32_e32 v89, v89, v90
	v_add_f32_e32 v102, v88, v89
	v_cvt_pk_bf16_f32 v88, v98, v92
	v_lshlrev_b32_e32 v92, 16, v168
	v_cvt_pk_bf16_f32 v89, v93, v94
	v_fmac_f32_e32 v92, 0x3d000000, v84
	v_and_b32_e32 v84, 0xffff0000, v168
	v_and_b32_e32 v93, 0xffff0000, v169
	v_cvt_pk_bf16_f32 v90, v95, v99
	v_fmac_f32_e32 v84, 0x3d000000, v85
	v_lshlrev_b32_e32 v85, 16, v169
	v_fmac_f32_e32 v93, 0x3d000000, v87
	v_lshlrev_b32_e32 v94, 16, v170
	v_and_b32_e32 v95, 0xffff0000, v170
	v_fmac_f32_e32 v85, 0x3d000000, v86
	v_fmac_f32_e32 v94, 0x3d000000, v80
	v_fmac_f32_e32 v95, 0x3d000000, v81
	v_and_b32_e32 v99, 0xffff0000, v171
	v_mul_f32_e32 v80, v84, v84
	v_mul_f32_e32 v81, v93, v93
	v_lshlrev_b32_e32 v98, 16, v171
	v_fmac_f32_e32 v99, 0x3d000000, v83
	v_fmac_f32_e32 v80, v92, v92
	v_fmac_f32_e32 v81, v85, v85
	v_fmac_f32_e32 v98, 0x3d000000, v82
	v_add_f32_e32 v80, v80, v81
	v_mul_f32_e32 v81, v95, v95
	v_mul_f32_e32 v82, v99, v99
	v_fmac_f32_e32 v81, v94, v94
	v_fmac_f32_e32 v82, v98, v98
	v_add_f32_e32 v81, v81, v82
	v_add_f32_e32 v80, v80, v81
	v_add_f32_e32 v83, v102, v80
	v_cvt_pk_bf16_f32 v91, v100, v101
	ds_bpermute_b32 v100, v112, v83
	s_waitcnt lgkmcnt(1)
	v_lshlrev_b64 v[96:97], 11, v[208:209]
	v_lshl_add_u64 v[80:81], v[96:97], 1, s[74:75]
	v_lshl_add_u64 v[86:87], v[196:197], 1, v[80:81]
	global_store_dwordx4 v[86:87], v[88:91], off sc1
	s_waitcnt lgkmcnt(0)
	v_add_f32_e32 v80, v83, v100
	ds_bpermute_b32 v81, v113, v80
	v_cvt_pk_bf16_f32 v82, v92, v84
	v_cvt_pk_bf16_f32 v83, v85, v93
	v_cvt_pk_bf16_f32 v84, v94, v95
	v_cvt_pk_bf16_f32 v85, v98, v99
	global_store_dwordx4 v[86:87], v[82:85], off offset:256 sc1
	s_and_saveexec_b64 s[6:7], vcc
	s_cbranch_execz .LBB0_632
	v_lshl_add_u64 v[82:83], v[208:209], 2, s[66:67]
	s_waitcnt lgkmcnt(0)
	v_add_f32_e32 v80, v80, v81
	global_atomic_add_f32 v[82:83], v80, off
.LBB0_632:
	s_or_b64 exec, exec, s[6:7]
	v_lshlrev_b32_e32 v82, 16, v164
	v_fmac_f32_e32 v82, 0x3d000000, v76
	v_and_b32_e32 v76, 0xffff0000, v164
	v_fmac_f32_e32 v76, 0x3d000000, v77
	v_lshlrev_b32_e32 v77, 16, v165
	v_fmac_f32_e32 v77, 0x3d000000, v78
	v_and_b32_e32 v78, 0xffff0000, v165
	v_fmac_f32_e32 v78, 0x3d000000, v79
	v_lshlrev_b32_e32 v79, 16, v166
	v_and_b32_e32 v83, 0xffff0000, v166
	v_fmac_f32_e32 v79, 0x3d000000, v72
	v_fmac_f32_e32 v83, 0x3d000000, v73
	v_and_b32_e32 v85, 0xffff0000, v167
	v_mul_f32_e32 v72, v76, v76
	v_mul_f32_e32 v73, v78, v78
	v_lshlrev_b32_e32 v84, 16, v167
	v_fmac_f32_e32 v85, 0x3d000000, v75
	v_fmac_f32_e32 v72, v82, v82
	v_fmac_f32_e32 v73, v77, v77
	v_fmac_f32_e32 v84, 0x3d000000, v74
	v_add_f32_e32 v72, v72, v73
	v_mul_f32_e32 v73, v83, v83
	v_mul_f32_e32 v74, v85, v85
	v_fmac_f32_e32 v73, v79, v79
	v_fmac_f32_e32 v74, v84, v84
	v_add_f32_e32 v73, v73, v74
	v_add_f32_e32 v86, v72, v73
	v_cvt_pk_bf16_f32 v72, v82, v76
	v_lshlrev_b32_e32 v76, 16, v160
	v_cvt_pk_bf16_f32 v73, v77, v78
	v_fmac_f32_e32 v76, 0x3d000000, v68
	v_and_b32_e32 v68, 0xffff0000, v160
	v_and_b32_e32 v77, 0xffff0000, v161
	v_cvt_pk_bf16_f32 v74, v79, v83
	v_fmac_f32_e32 v68, 0x3d000000, v69
	v_lshlrev_b32_e32 v69, 16, v161
	v_fmac_f32_e32 v77, 0x3d000000, v71
	v_lshlrev_b32_e32 v78, 16, v162
	v_and_b32_e32 v79, 0xffff0000, v162
	v_fmac_f32_e32 v69, 0x3d000000, v70
	v_fmac_f32_e32 v78, 0x3d000000, v64
	v_fmac_f32_e32 v79, 0x3d000000, v65
	v_and_b32_e32 v83, 0xffff0000, v163
	v_mul_f32_e32 v64, v68, v68
	v_mul_f32_e32 v65, v77, v77
	v_lshlrev_b32_e32 v82, 16, v163
	v_fmac_f32_e32 v83, 0x3d000000, v67
	v_fmac_f32_e32 v64, v76, v76
	v_fmac_f32_e32 v65, v69, v69
	v_fmac_f32_e32 v82, 0x3d000000, v66
	v_add_f32_e32 v64, v64, v65
	v_mul_f32_e32 v65, v79, v79
	v_mul_f32_e32 v66, v83, v83
	v_fmac_f32_e32 v65, v78, v78
	v_fmac_f32_e32 v66, v82, v82
	v_add_f32_e32 v65, v65, v66
	v_add_f32_e32 v64, v64, v65
	v_add_f32_e32 v67, v86, v64
	v_cvt_pk_bf16_f32 v75, v84, v85
	ds_bpermute_b32 v84, v112, v67
	s_waitcnt lgkmcnt(1)
	v_lshlrev_b64 v[80:81], 11, v[206:207]
	v_lshl_add_u64 v[64:65], v[80:81], 1, s[74:75]
	v_lshl_add_u64 v[70:71], v[196:197], 1, v[64:65]
	global_store_dwordx4 v[70:71], v[72:75], off sc1
	s_waitcnt lgkmcnt(0)
	v_add_f32_e32 v64, v67, v84
	ds_bpermute_b32 v65, v113, v64
	v_cvt_pk_bf16_f32 v66, v76, v68
	v_cvt_pk_bf16_f32 v67, v69, v77
	v_cvt_pk_bf16_f32 v68, v78, v79
	v_cvt_pk_bf16_f32 v69, v82, v83
	global_store_dwordx4 v[70:71], v[66:69], off offset:256 sc1
	s_and_saveexec_b64 s[6:7], vcc
	s_cbranch_execz .LBB0_634
	v_lshl_add_u64 v[66:67], v[206:207], 2, s[66:67]
	s_waitcnt lgkmcnt(0)
	v_add_f32_e32 v64, v64, v65
	global_atomic_add_f32 v[66:67], v64, off
;     __device__ __forceinline__ const char* b(const Unit& u) const { return (const char*)Bt + (size_t)u.pn * 2 * hB() + (size_t)(u.pm >> gshift) * goff; }
;     __device__ __forceinline__ const char* b(const Unit& u) const { return (const char*)Bt + (size_t)((u.pn >> 4) * 4096 + (u.pn & 15) * 16) * 1024 * 2 + (size_t)(u.pm >> 1) * 512; }
;     __device__ __forceinline__ const char* b(const Unit& u) const { return (const char*)Bt + ((size_t)(((u.pm >> 4) * 1024 + u.pn * 256) * 16 + (u.pm & 15)) * 512) * 2; }
;     __device__ __forceinline__ void operator()(const f32x4 (&acc)[2][2][4][2], const Unit& u, int wr, int wc, int fr, int fq) const {
;     ...
; #pragma unroll
;         for (int ai = 0; ai < 2; ++ai)
; #pragma unroll
;             for (int m = 0; m < 4; ++m) { const int r = row0 + ai * HALF + m * 16; const size_t off = (size_t)r * ldc + col0; float s = 0.f;
; #pragma unroll
;                 for (int bj = 0; bj < 2; ++bj) { const u32x4 b = bv[ai][m][bj];
;                     f32x4 o0, o1;
;                     o0[0] = __builtin_fmaf(acc[ai][bj][m][0][0], asc, __builtin_bit_cast(float, b.x << 16)); o0[1] = __builtin_fmaf(acc[ai][bj][m][0][1], asc, __builtin_bit_cast(float, b.x & 0xffff0000u));
;                     o0[2] = __builtin_fmaf(acc[ai][bj][m][0][2], asc, __builtin_bit_cast(float, b.y << 16)); o0[3] = __builtin_fmaf(acc[ai][bj][m][0][3], asc, __builtin_bit_cast(float, b.y & 0xffff0000u));
;                     o1[0] = __builtin_fmaf(acc[ai][bj][m][1][0], asc, __builtin_bit_cast(float, b.z << 16)); o1[1] = __builtin_fmaf(acc[ai][bj][m][1][1], asc, __builtin_bit_cast(float, b.z & 0xffff0000u));
;                     o1[2] = __builtin_fmaf(acc[ai][bj][m][1][2], asc, __builtin_bit_cast(float, b.w << 16)); o1[3] = __builtin_fmaf(acc[ai][bj][m][1][3], asc, __builtin_bit_cast(float, b.w & 0xffff0000u));
;                     s += ((o0[0] * o0[0] + o0[1] * o0[1]) + (o0[2] * o0[2] + o0[3] * o0[3])) + ((o1[0] * o1[0] + o1[1] * o1[1]) + (o1[2] * o1[2] + o1[3] * o1[3]));
;                     u32x4 w; w.x = cvt_pk_bf16(o0[0], o0[1]); w.y = cvt_pk_bf16(o0[2], o0[3]); w.z = cvt_pk_bf16(o1[0], o1[1]); w.w = cvt_pk_bf16(o1[2], o1[3]);
;                     *(u32x4*)(outb + off + bj * HALF) = w; }
;                 s += __shfl_xor(s, 16); s += __shfl_xor(s, 32);
;                 if (fq == 0) atomicAdd(ssq + r, s); }
.LBB0_634:
	s_or_b64 exec, exec, s[6:7]
	v_lshlrev_b32_e32 v66, 16, v156
	v_fmac_f32_e32 v66, 0x3d000000, v60
	v_and_b32_e32 v60, 0xffff0000, v156
	v_fmac_f32_e32 v60, 0x3d000000, v61
	v_lshlrev_b32_e32 v61, 16, v157
	v_fmac_f32_e32 v61, 0x3d000000, v62
	v_and_b32_e32 v62, 0xffff0000, v157
	v_fmac_f32_e32 v62, 0x3d000000, v63
	v_lshlrev_b32_e32 v63, 16, v158
	v_and_b32_e32 v67, 0xffff0000, v158
	v_fmac_f32_e32 v63, 0x3d000000, v56
	v_fmac_f32_e32 v67, 0x3d000000, v57
	v_and_b32_e32 v69, 0xffff0000, v159
	v_mul_f32_e32 v56, v60, v60
	v_mul_f32_e32 v57, v62, v62
	v_lshlrev_b32_e32 v68, 16, v159
	v_fmac_f32_e32 v69, 0x3d000000, v59
	v_fmac_f32_e32 v56, v66, v66
	v_fmac_f32_e32 v57, v61, v61
	v_fmac_f32_e32 v68, 0x3d000000, v58
	v_add_f32_e32 v56, v56, v57
	v_mul_f32_e32 v57, v67, v67
	v_mul_f32_e32 v58, v69, v69
	v_fmac_f32_e32 v57, v63, v63
	v_fmac_f32_e32 v58, v68, v68
	v_add_f32_e32 v57, v57, v58
	v_add_f32_e32 v70, v56, v57
	v_cvt_pk_bf16_f32 v56, v66, v60
	v_lshlrev_b32_e32 v60, 16, v152
	v_cvt_pk_bf16_f32 v57, v61, v62
	v_fmac_f32_e32 v60, 0x3d000000, v52
	v_and_b32_e32 v52, 0xffff0000, v152
	v_and_b32_e32 v61, 0xffff0000, v153
	v_cvt_pk_bf16_f32 v58, v63, v67
	v_fmac_f32_e32 v52, 0x3d000000, v53
	v_lshlrev_b32_e32 v53, 16, v153
	v_fmac_f32_e32 v61, 0x3d000000, v55
	v_lshlrev_b32_e32 v62, 16, v154
	v_and_b32_e32 v63, 0xffff0000, v154
	v_fmac_f32_e32 v53, 0x3d000000, v54
	v_fmac_f32_e32 v62, 0x3d000000, v48
	v_fmac_f32_e32 v63, 0x3d000000, v49
	v_and_b32_e32 v67, 0xffff0000, v155
	v_mul_f32_e32 v48, v52, v52
	v_mul_f32_e32 v49, v61, v61
	v_lshlrev_b32_e32 v66, 16, v155
	v_fmac_f32_e32 v67, 0x3d000000, v51
	v_fmac_f32_e32 v48, v60, v60
	v_fmac_f32_e32 v49, v53, v53
	v_fmac_f32_e32 v66, 0x3d000000, v50
	v_add_f32_e32 v48, v48, v49
	v_mul_f32_e32 v49, v63, v63
	v_mul_f32_e32 v50, v67, v67
	v_fmac_f32_e32 v49, v62, v62
	v_fmac_f32_e32 v50, v66, v66
	v_add_f32_e32 v49, v49, v50
	v_add_f32_e32 v48, v48, v49
	v_add_f32_e32 v51, v70, v48
	v_cvt_pk_bf16_f32 v59, v68, v69
	ds_bpermute_b32 v68, v112, v51
	s_waitcnt lgkmcnt(1)
	v_lshlrev_b64 v[64:65], 11, v[204:205]
	v_lshl_add_u64 v[48:49], v[64:65], 1, s[74:75]
	v_lshl_add_u64 v[54:55], v[196:197], 1, v[48:49]
	global_store_dwordx4 v[54:55], v[56:59], off sc1
	s_waitcnt lgkmcnt(0)
	v_add_f32_e32 v48, v51, v68
	ds_bpermute_b32 v49, v113, v48
	v_cvt_pk_bf16_f32 v50, v60, v52
	v_cvt_pk_bf16_f32 v51, v53, v61
	v_cvt_pk_bf16_f32 v52, v62, v63
	v_cvt_pk_bf16_f32 v53, v66, v67
	global_store_dwordx4 v[54:55], v[50:53], off offset:256 sc1
	s_and_saveexec_b64 s[6:7], vcc
	s_cbranch_execz .LBB0_636
	v_lshl_add_u64 v[50:51], v[204:205], 2, s[66:67]
	s_waitcnt lgkmcnt(0)
	v_add_f32_e32 v48, v48, v49
	global_atomic_add_f32 v[50:51], v48, off
.LBB0_636:
	s_or_b64 exec, exec, s[6:7]
	v_lshlrev_b32_e32 v50, 16, v148
	v_fmac_f32_e32 v50, 0x3d000000, v44
	v_and_b32_e32 v44, 0xffff0000, v148
	v_fmac_f32_e32 v44, 0x3d000000, v45
	v_lshlrev_b32_e32 v45, 16, v149
	v_fmac_f32_e32 v45, 0x3d000000, v46
	v_and_b32_e32 v46, 0xffff0000, v149
	v_fmac_f32_e32 v46, 0x3d000000, v47
	v_lshlrev_b32_e32 v47, 16, v150
	v_and_b32_e32 v51, 0xffff0000, v150
	v_fmac_f32_e32 v47, 0x3d000000, v40
	v_fmac_f32_e32 v51, 0x3d000000, v41
	v_and_b32_e32 v53, 0xffff0000, v151
	v_mul_f32_e32 v40, v44, v44
	v_mul_f32_e32 v41, v46, v46
	v_lshlrev_b32_e32 v52, 16, v151
	v_fmac_f32_e32 v53, 0x3d000000, v43
	v_fmac_f32_e32 v40, v50, v50
	v_fmac_f32_e32 v41, v45, v45
	v_fmac_f32_e32 v52, 0x3d000000, v42
	v_add_f32_e32 v40, v40, v41
	v_mul_f32_e32 v41, v51, v51
	v_mul_f32_e32 v42, v53, v53
	v_fmac_f32_e32 v41, v47, v47
	v_fmac_f32_e32 v42, v52, v52
	v_add_f32_e32 v41, v41, v42
	v_add_f32_e32 v54, v40, v41
	v_cvt_pk_bf16_f32 v40, v50, v44
	v_lshlrev_b32_e32 v44, 16, v144
	v_cvt_pk_bf16_f32 v41, v45, v46
	v_fmac_f32_e32 v44, 0x3d000000, v36
	v_and_b32_e32 v36, 0xffff0000, v144
	v_and_b32_e32 v45, 0xffff0000, v145
	v_cvt_pk_bf16_f32 v42, v47, v51
	v_fmac_f32_e32 v36, 0x3d000000, v37
	v_lshlrev_b32_e32 v37, 16, v145
	v_fmac_f32_e32 v45, 0x3d000000, v39
	v_lshlrev_b32_e32 v46, 16, v146
	v_and_b32_e32 v47, 0xffff0000, v146
	v_fmac_f32_e32 v37, 0x3d000000, v38
	v_fmac_f32_e32 v46, 0x3d000000, v32
	v_fmac_f32_e32 v47, 0x3d000000, v33
	v_and_b32_e32 v51, 0xffff0000, v147
	v_mul_f32_e32 v32, v36, v36
	v_mul_f32_e32 v33, v45, v45
	v_lshlrev_b32_e32 v50, 16, v147
	v_fmac_f32_e32 v51, 0x3d000000, v35
	v_fmac_f32_e32 v32, v44, v44
	v_fmac_f32_e32 v33, v37, v37
	v_fmac_f32_e32 v50, 0x3d000000, v34
	v_add_f32_e32 v32, v32, v33
	v_mul_f32_e32 v33, v47, v47
	v_mul_f32_e32 v34, v51, v51
	v_fmac_f32_e32 v33, v46, v46
	v_fmac_f32_e32 v34, v50, v50
	v_add_f32_e32 v33, v33, v34
	v_add_f32_e32 v32, v32, v33
	v_add_f32_e32 v35, v54, v32
	v_cvt_pk_bf16_f32 v43, v52, v53
	ds_bpermute_b32 v52, v112, v35
	s_waitcnt lgkmcnt(1)
	v_lshlrev_b64 v[48:49], 11, v[202:203]
	v_lshl_add_u64 v[32:33], v[48:49], 1, s[74:75]
	v_lshl_add_u64 v[38:39], v[196:197], 1, v[32:33]
	global_store_dwordx4 v[38:39], v[40:43], off sc1
	s_waitcnt lgkmcnt(0)
	v_add_f32_e32 v32, v35, v52
	ds_bpermute_b32 v33, v113, v32
	v_cvt_pk_bf16_f32 v34, v44, v36
	v_cvt_pk_bf16_f32 v35, v37, v45
	v_cvt_pk_bf16_f32 v36, v46, v47
	v_cvt_pk_bf16_f32 v37, v50, v51
	global_store_dwordx4 v[38:39], v[34:37], off offset:256 sc1
	s_and_saveexec_b64 s[6:7], vcc
	s_cbranch_execz .LBB0_638
	v_lshl_add_u64 v[34:35], v[202:203], 2, s[66:67]
	s_waitcnt lgkmcnt(0)
	v_add_f32_e32 v32, v32, v33
	global_atomic_add_f32 v[34:35], v32, off
;     __device__ __forceinline__ const char* b(const Unit& u) const { return (const char*)Bt + (size_t)u.pn * 2 * hB() + (size_t)(u.pm >> gshift) * goff; }
;     __device__ __forceinline__ const char* b(const Unit& u) const { return (const char*)Bt + (size_t)((u.pn >> 4) * 4096 + (u.pn & 15) * 16) * 1024 * 2 + (size_t)(u.pm >> 1) * 512; }
;     __device__ __forceinline__ const char* b(const Unit& u) const { return (const char*)Bt + ((size_t)(((u.pm >> 4) * 1024 + u.pn * 256) * 16 + (u.pm & 15)) * 512) * 2; }
;     __device__ __forceinline__ void operator()(const f32x4 (&acc)[2][2][4][2], const Unit& u, int wr, int wc, int fr, int fq) const {
;     ...
; #pragma unroll
;         for (int ai = 0; ai < 2; ++ai)
; #pragma unroll
;             for (int m = 0; m < 4; ++m) { const int r = row0 + ai * HALF + m * 16; const size_t off = (size_t)r * ldc + col0; float s = 0.f;
; #pragma unroll
;                 for (int bj = 0; bj < 2; ++bj) { const u32x4 b = bv[ai][m][bj];
;                     f32x4 o0, o1;
;                     o0[0] = __builtin_fmaf(acc[ai][bj][m][0][0], asc, __builtin_bit_cast(float, b.x << 16)); o0[1] = __builtin_fmaf(acc[ai][bj][m][0][1], asc, __builtin_bit_cast(float, b.x & 0xffff0000u));
;                     o0[2] = __builtin_fmaf(acc[ai][bj][m][0][2], asc, __builtin_bit_cast(float, b.y << 16)); o0[3] = __builtin_fmaf(acc[ai][bj][m][0][3], asc, __builtin_bit_cast(float, b.y & 0xffff0000u));
;                     o1[0] = __builtin_fmaf(acc[ai][bj][m][1][0], asc, __builtin_bit_cast(float, b.z << 16)); o1[1] = __builtin_fmaf(acc[ai][bj][m][1][1], asc, __builtin_bit_cast(float, b.z & 0xffff0000u));
;                     o1[2] = __builtin_fmaf(acc[ai][bj][m][1][2], asc, __builtin_bit_cast(float, b.w << 16)); o1[3] = __builtin_fmaf(acc[ai][bj][m][1][3], asc, __builtin_bit_cast(float, b.w & 0xffff0000u));
;                     s += ((o0[0] * o0[0] + o0[1] * o0[1]) + (o0[2] * o0[2] + o0[3] * o0[3])) + ((o1[0] * o1[0] + o1[1] * o1[1]) + (o1[2] * o1[2] + o1[3] * o1[3]));
;                     u32x4 w; w.x = cvt_pk_bf16(o0[0], o0[1]); w.y = cvt_pk_bf16(o0[2], o0[3]); w.z = cvt_pk_bf16(o1[0], o1[1]); w.w = cvt_pk_bf16(o1[2], o1[3]);
;                     *(u32x4*)(outb + off + bj * HALF) = w; }
;                 s += __shfl_xor(s, 16); s += __shfl_xor(s, 32);
;                 if (fq == 0) atomicAdd(ssq + r, s); }
.LBB0_638:
	s_or_b64 exec, exec, s[6:7]
	v_lshlrev_b32_e32 v34, 16, v140
	v_fmac_f32_e32 v34, 0x3d000000, v28
	v_and_b32_e32 v28, 0xffff0000, v140
	v_fmac_f32_e32 v28, 0x3d000000, v29
	v_lshlrev_b32_e32 v29, 16, v141
	v_fmac_f32_e32 v29, 0x3d000000, v30
	v_and_b32_e32 v30, 0xffff0000, v141
	v_fmac_f32_e32 v30, 0x3d000000, v31
	v_lshlrev_b32_e32 v31, 16, v142
	v_and_b32_e32 v35, 0xffff0000, v142
	v_fmac_f32_e32 v31, 0x3d000000, v24
	v_fmac_f32_e32 v35, 0x3d000000, v25
	v_and_b32_e32 v37, 0xffff0000, v143
	v_mul_f32_e32 v24, v28, v28
	v_mul_f32_e32 v25, v30, v30
	v_lshlrev_b32_e32 v36, 16, v143
	v_fmac_f32_e32 v37, 0x3d000000, v27
	v_fmac_f32_e32 v24, v34, v34
	v_fmac_f32_e32 v25, v29, v29
	v_fmac_f32_e32 v36, 0x3d000000, v26
	v_add_f32_e32 v24, v24, v25
	v_mul_f32_e32 v25, v35, v35
	v_mul_f32_e32 v26, v37, v37
	v_fmac_f32_e32 v25, v31, v31
	v_fmac_f32_e32 v26, v36, v36
	v_add_f32_e32 v25, v25, v26
	v_add_f32_e32 v38, v24, v25
	v_cvt_pk_bf16_f32 v24, v34, v28
	v_lshlrev_b32_e32 v28, 16, v136
	v_cvt_pk_bf16_f32 v25, v29, v30
	v_fmac_f32_e32 v28, 0x3d000000, v20
	v_and_b32_e32 v20, 0xffff0000, v136
	v_and_b32_e32 v29, 0xffff0000, v137
	v_cvt_pk_bf16_f32 v26, v31, v35
	v_fmac_f32_e32 v20, 0x3d000000, v21
	v_lshlrev_b32_e32 v21, 16, v137
	v_fmac_f32_e32 v29, 0x3d000000, v23
	v_lshlrev_b32_e32 v30, 16, v138
	v_and_b32_e32 v31, 0xffff0000, v138
	v_fmac_f32_e32 v21, 0x3d000000, v22
	v_fmac_f32_e32 v30, 0x3d000000, v16
	v_fmac_f32_e32 v31, 0x3d000000, v17
	v_and_b32_e32 v35, 0xffff0000, v139
	v_mul_f32_e32 v16, v20, v20
	v_mul_f32_e32 v17, v29, v29
	v_lshlrev_b32_e32 v34, 16, v139
	v_fmac_f32_e32 v35, 0x3d000000, v19
	v_fmac_f32_e32 v16, v28, v28
	v_fmac_f32_e32 v17, v21, v21
	v_fmac_f32_e32 v34, 0x3d000000, v18
	v_add_f32_e32 v16, v16, v17
	v_mul_f32_e32 v17, v31, v31
	v_mul_f32_e32 v18, v35, v35
	v_fmac_f32_e32 v17, v30, v30
	v_fmac_f32_e32 v18, v34, v34
	v_add_f32_e32 v17, v17, v18
	v_add_f32_e32 v16, v16, v17
	v_add_f32_e32 v19, v38, v16
	v_cvt_pk_bf16_f32 v27, v36, v37
	ds_bpermute_b32 v36, v112, v19
	s_waitcnt lgkmcnt(1)
	v_lshlrev_b64 v[32:33], 11, v[200:201]
	v_lshl_add_u64 v[16:17], v[32:33], 1, s[74:75]
	v_lshl_add_u64 v[22:23], v[196:197], 1, v[16:17]
	global_store_dwordx4 v[22:23], v[24:27], off sc1
	s_waitcnt lgkmcnt(0)
	v_add_f32_e32 v16, v19, v36
	ds_bpermute_b32 v17, v113, v16
	v_cvt_pk_bf16_f32 v18, v28, v20
	v_cvt_pk_bf16_f32 v19, v21, v29
	v_cvt_pk_bf16_f32 v20, v30, v31
	v_cvt_pk_bf16_f32 v21, v34, v35
	global_store_dwordx4 v[22:23], v[18:21], off offset:256 sc1
	s_and_saveexec_b64 s[6:7], vcc
	s_cbranch_execz .LBB0_640
	v_lshl_add_u64 v[18:19], v[200:201], 2, s[66:67]
	s_waitcnt lgkmcnt(0)
	v_add_f32_e32 v16, v16, v17
	global_atomic_add_f32 v[18:19], v16, off
.LBB0_640:
	s_or_b64 exec, exec, s[6:7]
	v_lshlrev_b32_e32 v18, 16, v132
	v_fmac_f32_e32 v18, 0x3d000000, v12
	v_and_b32_e32 v12, 0xffff0000, v132
	v_fmac_f32_e32 v12, 0x3d000000, v13
	v_lshlrev_b32_e32 v13, 16, v133
	v_fmac_f32_e32 v13, 0x3d000000, v14
	v_and_b32_e32 v14, 0xffff0000, v133
	v_fmac_f32_e32 v14, 0x3d000000, v15
	v_lshlrev_b32_e32 v15, 16, v134
	v_and_b32_e32 v19, 0xffff0000, v134
	v_fmac_f32_e32 v15, 0x3d000000, v8
	v_fmac_f32_e32 v19, 0x3d000000, v9
	v_and_b32_e32 v21, 0xffff0000, v135
	v_mul_f32_e32 v8, v12, v12
	v_mul_f32_e32 v9, v14, v14
	v_lshlrev_b32_e32 v20, 16, v135
	v_fmac_f32_e32 v21, 0x3d000000, v11
	v_fmac_f32_e32 v8, v18, v18
	v_fmac_f32_e32 v9, v13, v13
	v_fmac_f32_e32 v20, 0x3d000000, v10
	v_add_f32_e32 v8, v8, v9
	v_mul_f32_e32 v9, v19, v19
	v_mul_f32_e32 v10, v21, v21
	v_fmac_f32_e32 v9, v15, v15
	v_fmac_f32_e32 v10, v20, v20
	v_add_f32_e32 v9, v9, v10
	v_add_f32_e32 v22, v8, v9
	v_cvt_pk_bf16_f32 v8, v18, v12
	v_lshlrev_b32_e32 v12, 16, v128
	v_cvt_pk_bf16_f32 v9, v13, v14
	v_fmac_f32_e32 v12, 0x3d000000, v4
	v_and_b32_e32 v4, 0xffff0000, v128
	v_and_b32_e32 v13, 0xffff0000, v129
	v_cvt_pk_bf16_f32 v10, v15, v19
	v_fmac_f32_e32 v4, 0x3d000000, v5
	v_lshlrev_b32_e32 v5, 16, v129
	v_fmac_f32_e32 v13, 0x3d000000, v7
	v_lshlrev_b32_e32 v14, 16, v130
	v_and_b32_e32 v15, 0xffff0000, v130
	v_fmac_f32_e32 v5, 0x3d000000, v6
	v_fmac_f32_e32 v14, 0x3d000000, v0
	v_fmac_f32_e32 v15, 0x3d000000, v1
	v_and_b32_e32 v19, 0xffff0000, v131
	v_mul_f32_e32 v0, v4, v4
	v_mul_f32_e32 v1, v13, v13
	v_lshlrev_b32_e32 v18, 16, v131
	v_fmac_f32_e32 v19, 0x3d000000, v3
	v_fmac_f32_e32 v0, v12, v12
	v_fmac_f32_e32 v1, v5, v5
	v_fmac_f32_e32 v18, 0x3d000000, v2
	v_add_f32_e32 v0, v0, v1
	v_mul_f32_e32 v1, v15, v15
	v_mul_f32_e32 v2, v19, v19
	v_fmac_f32_e32 v1, v14, v14
	v_fmac_f32_e32 v2, v18, v18
	v_add_f32_e32 v1, v1, v2
	v_add_f32_e32 v0, v0, v1
	v_add_f32_e32 v3, v22, v0
	v_cvt_pk_bf16_f32 v11, v20, v21
	ds_bpermute_b32 v20, v112, v3
	s_waitcnt lgkmcnt(1)
	v_lshlrev_b64 v[16:17], 11, v[198:199]
	v_lshl_add_u64 v[0:1], v[16:17], 1, s[74:75]
	v_lshl_add_u64 v[6:7], v[196:197], 1, v[0:1]
	global_store_dwordx4 v[6:7], v[8:11], off sc1
	s_waitcnt lgkmcnt(0)
	v_add_f32_e32 v0, v3, v20
	ds_bpermute_b32 v1, v113, v0
	v_cvt_pk_bf16_f32 v2, v12, v4
	v_cvt_pk_bf16_f32 v3, v5, v13
	v_cvt_pk_bf16_f32 v4, v14, v15
	v_cvt_pk_bf16_f32 v5, v18, v19
	global_store_dwordx4 v[6:7], v[2:5], off offset:256 sc1
	s_and_saveexec_b64 s[6:7], vcc
	s_cbranch_execz .LBB0_642
	v_lshl_add_u64 v[2:3], v[198:199], 2, s[66:67]
	s_waitcnt lgkmcnt(0)
	v_add_f32_e32 v0, v0, v1
	global_atomic_add_f32 v[2:3], v0, off

; __device__ __forceinline__ unsigned xb_add(unsigned* p, unsigned v) { return __hip_atomic_fetch_add(p, v, __ATOMIC_RELAXED, __HIP_MEMORY_SCOPE_AGENT); }
; __device__ __forceinline__ void xcd_barrier(const XcdBarrier& b, const int wave) {
;     ...
;         if (old + 1u == (gen + 1u) * nloc) {
;             __builtin_amdgcn_fence(__ATOMIC_RELEASE, "agent");
;             asm volatile("s_waitcnt vmcnt(0)" ::: "memory");
;             const unsigned og = xb_add(&bar[XB_TOP], 1u);
;             const unsigned tg = og / nx;
;             if (og + 1u == (tg + 1u) * nx) xb_add(&bar[XB_TOPGEN], 1u);
.LBB0_679:
	s_andn2_saveexec_b64 s[6:7], s[6:7]
	s_cbranch_execz .LBB0_699
	s_mov_b64 s[6:7], exec
	s_waitcnt lgkmcnt(0)
	s_waitcnt vmcnt(0)
	v_mbcnt_lo_u32_b32 v1, s6, 0
	v_mbcnt_hi_u32_b32 v1, s7, v1
	v_cmp_eq_u32_e32 vcc, 0, v1
	s_and_saveexec_b64 s[8:9], vcc
	s_cbranch_execz .LBB0_682
	s_bcnt1_i32_b64 s6, s[6:7]
	v_mov_b32_e32 v2, 0x7000
	v_mov_b32_e32 v3, s6
	global_atomic_add v2, v2, v3, s[94:95] offset:1024 sc0
